# attention softmax row-max tree rebuilt with v_max3 (7 v_max3 + 1 v_max instead of 21 ops per 16 scores, canonicalising maxes dropped); MFMA-to-VALU wait states re-checked
# baseline (speedup 1.0000x reference)
; #define LAS __attribute__((address_space(3)))
; #define MFMA16(a_, b_, c_) __builtin_amdgcn_mfma_f32_16x16x32_bf16((a_), (b_), (c_), 0, 0, 0)
; __device__ __forceinline__ s16x4 tr_read(LAS unsigned char* p) { return __builtin_bit_cast(s16x4, __builtin_amdgcn_ds_read_tr16_b64_v4i16((LAS v4i16_t*)p)); }
; __device__ __forceinline__ bf16x8 pack8(const f32x4& lo, const f32x4& hi) { u32x4 w; w.x = cvt_pk_bf16(lo[0], lo[1]); w.y = cvt_pk_bf16(lo[2], lo[3]); w.z = cvt_pk_bf16(hi[0], hi[1]); w.w = cvt_pk_bf16(hi[2], hi[3]); return __builtin_bit_cast(bf16x8, w); }
; __device__ __forceinline__ void attn_prompt_unit(ArgsK& a, LAS unsigned char* lds, int b, int h, int qb, int tid, int wave, int lane) {
;     ...
;             for (int qq = 0; qq < 2; ++qq) { float mx = fmaxf(fmaxf(st[0][qq][0], st[0][qq][1]), fmaxf(st[0][qq][2], st[0][qq][3]));
; #pragma unroll
;                 for (int kb = 1; kb < 4; ++kb) mx = fmaxf(mx, fmaxf(fmaxf(st[kb][qq][0], st[kb][qq][1]), fmaxf(st[kb][qq][2], st[kb][qq][3])));
;                 mx = xmax16_32(mx);
;                 const float mnew = fmaxf(mrun[qq], mx), alpha = __builtin_amdgcn_exp2f(mrun[qq] - mnew); mrun[qq] = mnew; float ps = 0.f;
; #pragma unroll
;                 for (int kb = 0; kb < 4; ++kb)
; #pragma unroll
;                     for (int j = 0; j < 4; ++j) { const float p = __builtin_amdgcn_exp2f(st[kb][qq][j] - mnew); st[kb][qq][j] = p; ps += p; }
;                 lrun[qq] = lrun[qq] * alpha + ps;
; #pragma unroll
;                 for (int d = 0; d < 4; ++d) o[qq][d] = o[qq][d] * alpha; }
; #pragma unroll
;             for (int c = 0; c < 2; ++c) { bf16x8 pf[2];
; #pragma unroll
;                 for (int qq = 0; qq < 2; ++qq) pf[qq] = pack8(st[2 * c][qq], st[2 * c + 1][qq]);
; #pragma unroll
;                 for (int d = 0; d < 4; ++d) { LAS unsigned char* vp = bufc + AT_V + (32 * c + quad * 4 + (l15 >> 2)) * 160 + d * 32 + (lane & 3) * 8;
;                     const s16x4 r1 = tr_read(vp), r2 = tr_read(vp + 16 * 160);
;                     const bf16x8 vf = (bf16x8){r1[0], r1[1], r1[2], r1[3], r2[0], r2[1], r2[2], r2[3]};
; #pragma unroll
;                     for (int qq = 0; qq < 2; ++qq) o[qq][d] = MFMA16(vf, pf[qq], o[qq][d]); } }
.LBB0_235:
	s_nop 5
	v_max3_f32 v6, v2, v3, v4
	v_max3_f32 v7, v5, v70, v71
	v_max3_f32 v6, v6, v72, v73
	v_max3_f32 v7, v7, v74, v75
	v_max3_f32 v6, v6, v76, v77
	v_max3_f32 v7, v7, v78, v79
	v_max3_f32 v6, v6, v80, v81
	v_max_f32_e32 v6, v6, v7
	v_mov_b32_e32 v7, v6
	s_nop 1
	v_permlane16_swap_b32_e32 v6, v7
	v_max_f32_e32 v6, v6, v7
	v_mov_b32_e32 v7, v6
	s_nop 1
	v_permlane32_swap_b32_e32 v6, v7
	v_max3_f32 v6, v140, v6, v7
	v_sub_f32_e32 v7, v140, v6
	v_exp_f32_e32 v22, v7
	v_sub_f32_e32 v7, v70, v6
	v_exp_f32_e32 v86, v7
	v_sub_f32_e32 v7, v71, v6
	v_exp_f32_e32 v88, v7
	v_sub_f32_e32 v7, v72, v6
	v_exp_f32_e32 v90, v7
	v_sub_f32_e32 v7, v73, v6
	v_exp_f32_e32 v92, v7
	v_sub_f32_e32 v7, v74, v6
	v_exp_f32_e32 v94, v7
	v_sub_f32_e32 v7, v75, v6
	v_exp_f32_e32 v96, v7
	v_sub_f32_e32 v7, v76, v6
	v_exp_f32_e32 v98, v7
	v_sub_f32_e32 v7, v77, v6
	v_exp_f32_e32 v100, v7
	v_sub_f32_e32 v7, v78, v6
	v_sub_f32_e32 v2, v2, v6
	v_exp_f32_e32 v70, v7
	v_sub_f32_e32 v7, v79, v6
	v_exp_f32_e32 v78, v2
	v_sub_f32_e32 v2, v3, v6
	v_exp_f32_e32 v72, v7
	v_sub_f32_e32 v7, v80, v6
	v_exp_f32_e32 v80, v2
	v_sub_f32_e32 v2, v4, v6
	v_exp_f32_e32 v74, v7
	v_sub_f32_e32 v7, v81, v6
	v_exp_f32_e32 v82, v2
	v_sub_f32_e32 v2, v5, v6
	v_exp_f32_e32 v76, v7
	v_exp_f32_e32 v84, v2
	v_pk_mul_f32 v[16:17], v[56:57], v[22:23] op_sel_hi:[1,0]
	v_pk_mul_f32 v[14:15], v[54:55], v[22:23] op_sel_hi:[1,0]
	v_pk_mul_f32 v[20:21], v[52:53], v[22:23] op_sel_hi:[1,0]
	v_pk_mul_f32 v[18:19], v[50:51], v[22:23] op_sel_hi:[1,0]
	v_pk_mul_f32 v[8:9], v[60:61], v[22:23] op_sel_hi:[1,0]
	v_pk_mul_f32 v[6:7], v[58:59], v[22:23] op_sel_hi:[1,0]
	v_pk_mul_f32 v[4:5], v[64:65], v[22:23] op_sel_hi:[1,0]
	v_pk_mul_f32 v[2:3], v[62:63], v[22:23] op_sel_hi:[1,0]
	v_max3_f32 v23, v10, v11, v12
	v_max3_f32 v24, v13, v34, v35
	v_max3_f32 v23, v23, v36, v37
	v_max3_f32 v24, v24, v38, v39
	v_max3_f32 v23, v23, v40, v41
	v_max3_f32 v24, v24, v66, v67
	v_max3_f32 v23, v23, v68, v69
	v_max_f32_e32 v23, v23, v24
	v_mov_b32_e32 v24, v23
	s_nop 1
	v_permlane16_swap_b32_e32 v23, v24
	v_max_f32_e32 v23, v23, v24
	v_mov_b32_e32 v24, v23
	s_nop 1
	v_permlane32_swap_b32_e32 v23, v24
	v_max3_f32 v50, v0, v23, v24
	v_sub_f32_e32 v0, v0, v50
	v_exp_f32_e32 v23, v0
	v_sub_f32_e32 v0, v38, v50
	v_exp_f32_e32 v87, v0
	v_sub_f32_e32 v0, v39, v50
	v_exp_f32_e32 v89, v0
	v_sub_f32_e32 v0, v40, v50
	v_exp_f32_e32 v91, v0
	v_sub_f32_e32 v0, v41, v50
	v_exp_f32_e32 v93, v0
	v_sub_f32_e32 v0, v34, v50
	v_exp_f32_e32 v95, v0
	v_sub_f32_e32 v0, v35, v50
	v_exp_f32_e32 v97, v0
	v_sub_f32_e32 v0, v36, v50
	v_pk_add_f32 v[24:25], v[86:87], 0 op_sel_hi:[1,0]
	v_exp_f32_e32 v99, v0
	v_sub_f32_e32 v0, v37, v50
	v_pk_add_f32 v[24:25], v[88:89], v[24:25]
	v_exp_f32_e32 v101, v0
	v_sub_f32_e32 v0, v66, v50
	v_pk_add_f32 v[24:25], v[90:91], v[24:25]
	v_exp_f32_e32 v71, v0
	v_sub_f32_e32 v0, v67, v50
	v_pk_add_f32 v[24:25], v[92:93], v[24:25]
	v_exp_f32_e32 v73, v0
	v_sub_f32_e32 v0, v68, v50
	v_pk_add_f32 v[24:25], v[94:95], v[24:25]
	v_exp_f32_e32 v75, v0
	v_sub_f32_e32 v0, v69, v50
	v_pk_add_f32 v[24:25], v[96:97], v[24:25]
	v_exp_f32_e32 v77, v0
	v_sub_f32_e32 v0, v10, v50
	v_exp_f32_e32 v79, v0
	v_sub_f32_e32 v0, v11, v50
	v_pk_add_f32 v[10:11], v[98:99], v[24:25]
	v_exp_f32_e32 v81, v0
	v_pk_add_f32 v[10:11], v[100:101], v[10:11]
	v_sub_f32_e32 v0, v12, v50
	v_pk_add_f32 v[10:11], v[70:71], v[10:11]
	v_exp_f32_e32 v83, v0
	v_pk_add_f32 v[10:11], v[72:73], v[10:11]
	v_sub_f32_e32 v0, v13, v50
	v_pk_add_f32 v[10:11], v[74:75], v[10:11]
	v_exp_f32_e32 v85, v0
	v_pk_add_f32 v[10:11], v[76:77], v[10:11]
	v_mov_b32_e32 v0, v23
	v_pk_add_f32 v[10:11], v[78:79], v[10:11]
	v_pk_mul_f32 v[24:25], v[44:45], v[0:1] op_sel_hi:[1,0]
	v_pk_add_f32 v[10:11], v[80:81], v[10:11]
	v_cvt_pk_bf16_f32 v34, v86, v88
	v_cvt_pk_bf16_f32 v35, v90, v92
	v_cvt_pk_bf16_f32 v36, v94, v96
	v_cvt_pk_bf16_f32 v37, v98, v100
	v_cvt_pk_bf16_f32 v38, v87, v89
	s_nop 0
	v_pk_add_f32 v[10:11], v[82:83], v[10:11]
	v_cvt_pk_bf16_f32 v39, v91, v93
	v_cvt_pk_bf16_f32 v40, v95, v97
	v_cvt_pk_bf16_f32 v41, v99, v101
	v_pk_mul_f32 v[32:33], v[32:33], v[0:1] op_sel_hi:[1,0]
	v_pk_add_f32 v[10:11], v[84:85], v[10:11]
	v_pk_mul_f32 v[30:31], v[30:31], v[0:1] op_sel_hi:[1,0]
	v_pk_fma_f32 v[134:135], v[134:135], v[22:23], v[10:11]
	v_pk_mul_f32 v[22:23], v[42:43], v[0:1] op_sel_hi:[1,0]
	v_pk_mul_f32 v[10:11], v[46:47], v[0:1] op_sel_hi:[1,0]
	ds_read_b64_tr_b16 v[44:45], v221 offset:11776
	ds_read_b64_tr_b16 v[42:43], v221 offset:9216
	ds_read_b64_tr_b16 v[46:47], v221 offset:9248
	v_pk_mul_f32 v[12:13], v[48:49], v[0:1] op_sel_hi:[1,0]
	s_waitcnt lgkmcnt(1)
	v_mfma_f32_16x16x32_bf16 v[14:17], v[42:45], v[34:37], v[14:17]
	ds_read_b64_tr_b16 v[48:49], v221 offset:11808
	v_pk_mul_f32 v[28:29], v[28:29], v[0:1] op_sel_hi:[1,0]
	v_pk_mul_f32 v[26:27], v[26:27], v[0:1] op_sel_hi:[1,0]
	v_mfma_f32_16x16x32_bf16 v[30:33], v[42:45], v[38:41], v[30:33]
	ds_read_b64_tr_b16 v[42:43], v221 offset:9280
	ds_read_b64_tr_b16 v[44:45], v221 offset:11840
	s_waitcnt lgkmcnt(0)
	v_mfma_f32_16x16x32_bf16 v[6:9], v[42:45], v[34:37], v[6:9]
	v_mfma_f32_16x16x32_bf16 v[22:25], v[42:45], v[38:41], v[22:25]
	ds_read_b64_tr_b16 v[42:43], v221 offset:9312
	ds_read_b64_tr_b16 v[44:45], v221 offset:11872
	v_mfma_f32_16x16x32_bf16 v[18:21], v[46:49], v[34:37], v[18:21]
	v_mfma_f32_16x16x32_bf16 v[26:29], v[46:49], v[38:41], v[26:29]
	s_waitcnt lgkmcnt(0)
	v_mfma_f32_16x16x32_bf16 v[2:5], v[42:45], v[34:37], v[2:5]
	v_cvt_pk_bf16_f32 v34, v70, v72
	v_cvt_pk_bf16_f32 v35, v74, v76
	v_cvt_pk_bf16_f32 v36, v78, v80
	v_mfma_f32_16x16x32_bf16 v[10:13], v[42:45], v[38:41], v[10:13]
	v_cvt_pk_bf16_f32 v37, v82, v84
	v_cvt_pk_bf16_f32 v38, v71, v73
	v_cvt_pk_bf16_f32 v39, v75, v77
	v_cvt_pk_bf16_f32 v40, v79, v81
	v_cvt_pk_bf16_f32 v41, v83, v85
	ds_read_b64_tr_b16 v[44:45], v221 offset:16896
	ds_read_b64_tr_b16 v[42:43], v221 offset:14336
	ds_read_b64_tr_b16 v[46:47], v221 offset:14368
	s_waitcnt lgkmcnt(1)
	v_mfma_f32_16x16x32_bf16 v[54:57], v[42:45], v[34:37], v[14:17]
	ds_read_b64_tr_b16 v[48:49], v221 offset:16928
	s_nop 1
	ds_read_b64_tr_b16 v[14:15], v221 offset:14400
	ds_read_b64_tr_b16 v[16:17], v221 offset:16960
	s_waitcnt lgkmcnt(0)
	v_mfma_f32_16x16x32_bf16 v[58:61], v[14:17], v[34:37], v[6:9]
	s_nop 2
	ds_read_b64_tr_b16 v[6:7], v221 offset:14432
	ds_read_b64_tr_b16 v[8:9], v221 offset:16992
	v_mfma_f32_16x16x32_bf16 v[30:33], v[42:45], v[38:41], v[30:33]
	v_mfma_f32_16x16x32_bf16 v[50:53], v[46:49], v[34:37], v[18:21]
	v_mfma_f32_16x16x32_bf16 v[26:29], v[46:49], v[38:41], v[26:29]
	v_mfma_f32_16x16x32_bf16 v[42:45], v[14:17], v[38:41], v[22:25]
	s_waitcnt lgkmcnt(0)
	v_mfma_f32_16x16x32_bf16 v[62:65], v[6:9], v[34:37], v[2:5]
	v_mfma_f32_16x16x32_bf16 v[46:49], v[6:9], v[38:41], v[10:13]

; __device__ __forceinline__ void attn_prompt_unit(ArgsK& a, LAS unsigned char* lds, int b, int h, int qb, int tid, int wave, int lane) {
;     ...
;             for (int qq = 0; qq < 2; ++qq) { float mx = fmaxf(fmaxf(st[0][qq][0], st[0][qq][1]), fmaxf(st[0][qq][2], st[0][qq][3]));
; #pragma unroll
;                 for (int kb = 1; kb < 4; ++kb) mx = fmaxf(mx, fmaxf(fmaxf(st[kb][qq][0], st[kb][qq][1]), fmaxf(st[kb][qq][2], st[kb][qq][3])));
;                 mx = xmax16_32(mx);
;                 const float mnew = fmaxf(mrun[qq], mx), alpha = __builtin_amdgcn_exp2f(mrun[qq] - mnew); mrun[qq] = mnew; float ps = 0.f;
; #pragma unroll
;                 for (int kb = 0; kb < 4; ++kb)
; #pragma unroll
;                     for (int j = 0; j < 4; ++j) { const float p = __builtin_amdgcn_exp2f(st[kb][qq][j] - mnew); st[kb][qq][j] = p; ps += p; }
;                 lrun[qq] = lrun[qq] * alpha + ps;
; #pragma unroll
;                 for (int d = 0; d < 4; ++d) o[qq][d] = o[qq][d] * alpha; }
.LBB0_252:
	s_nop 0
	v_max3_f32 v0, v90, v91, v92
	v_max3_f32 v146, v93, v94, v95
	v_max3_f32 v0, v0, v96, v97
	v_max3_f32 v146, v146, v98, v99
	v_max3_f32 v0, v0, v100, v101
	v_max3_f32 v146, v146, v102, v103
	v_max3_f32 v0, v0, v104, v105
	v_max_f32_e32 v0, v0, v146
	v_mov_b32_e32 v146, v0
	s_nop 1
	v_permlane16_swap_b32_e32 v0, v146
	v_max_f32_e32 v0, v0, v146
	v_mov_b32_e32 v146, v0
	s_nop 1
	v_permlane32_swap_b32_e32 v0, v146
	v_max3_f32 v0, v172, v0, v146
	v_sub_f32_e32 v90, v90, v0
	v_exp_f32_e32 v176, v90
	v_sub_f32_e32 v90, v91, v0
	v_exp_f32_e32 v178, v90
	v_sub_f32_e32 v90, v92, v0
	v_exp_f32_e32 v180, v90
	v_sub_f32_e32 v90, v93, v0
	v_exp_f32_e32 v182, v90
	v_sub_f32_e32 v90, v94, v0
	v_exp_f32_e32 v184, v90
	v_sub_f32_e32 v90, v95, v0
	v_exp_f32_e32 v186, v90
	v_sub_f32_e32 v90, v96, v0
	v_exp_f32_e32 v188, v90
	v_sub_f32_e32 v90, v97, v0
	v_exp_f32_e32 v190, v90
	v_sub_f32_e32 v90, v98, v0
	v_exp_f32_e32 v94, v90
	v_sub_f32_e32 v90, v99, v0
	v_exp_f32_e32 v96, v90
	v_sub_f32_e32 v90, v100, v0
	v_sub_f32_e32 v146, v172, v0
	v_exp_f32_e32 v98, v90
	v_sub_f32_e32 v90, v101, v0
	v_exp_f32_e32 v146, v146
	v_exp_f32_e32 v100, v90
	v_sub_f32_e32 v90, v102, v0
	v_exp_f32_e32 v102, v90
	v_sub_f32_e32 v90, v103, v0
	v_exp_f32_e32 v172, v90
	v_sub_f32_e32 v90, v104, v0
	v_exp_f32_e32 v104, v90
	v_sub_f32_e32 v90, v105, v0
	v_exp_f32_e32 v174, v90
	v_pk_mul_f32 v[90:91], v[58:59], v[146:147] op_sel_hi:[1,0]
	v_pk_mul_f32 v[58:59], v[70:71], v[146:147] op_sel_hi:[1,0]
	v_pk_mul_f32 v[92:93], v[60:61], v[146:147] op_sel_hi:[1,0]
	v_pk_mul_f32 v[60:61], v[72:73], v[146:147] op_sel_hi:[1,0]
	v_max3_f32 v70, v74, v75, v76
	v_max3_f32 v71, v77, v78, v79
	v_max3_f32 v70, v70, v80, v81
	v_max3_f32 v71, v71, v82, v83
	v_max3_f32 v70, v70, v84, v85
	v_max3_f32 v71, v71, v86, v87
	v_max3_f32 v70, v70, v88, v89
	v_max_f32_e32 v70, v70, v71
	v_mov_b32_e32 v71, v70
	s_nop 1
	v_permlane16_swap_b32_e32 v70, v71
	v_max_f32_e32 v70, v70, v71
	v_mov_b32_e32 v71, v70
	s_nop 1
	v_permlane32_swap_b32_e32 v70, v71
	v_max3_f32 v225, v173, v70, v71
	v_sub_f32_e32 v70, v173, v225
	v_pk_mul_f32 v[68:69], v[68:69], v[146:147] op_sel_hi:[1,0]
	v_pk_mul_f32 v[66:67], v[66:67], v[146:147] op_sel_hi:[1,0]
	v_pk_mul_f32 v[64:65], v[64:65], v[146:147] op_sel_hi:[1,0]
	v_pk_mul_f32 v[62:63], v[62:63], v[146:147] op_sel_hi:[1,0]
	v_exp_f32_e32 v147, v70
	v_sub_f32_e32 v70, v78, v225
	v_exp_f32_e32 v177, v70
	v_sub_f32_e32 v70, v79, v225
	v_exp_f32_e32 v179, v70
	v_sub_f32_e32 v70, v80, v225
	v_exp_f32_e32 v181, v70
	v_sub_f32_e32 v70, v81, v225
	v_exp_f32_e32 v183, v70
	v_sub_f32_e32 v70, v74, v225
	v_exp_f32_e32 v185, v70
	v_sub_f32_e32 v70, v75, v225
	v_exp_f32_e32 v187, v70
	v_pk_add_f32 v[70:71], v[176:177], 0 op_sel_hi:[1,0]
	v_sub_f32_e32 v72, v76, v225
	v_pk_add_f32 v[70:71], v[178:179], v[70:71]
	v_exp_f32_e32 v189, v72
	v_pk_add_f32 v[70:71], v[180:181], v[70:71]
	v_sub_f32_e32 v72, v77, v225
	v_pk_add_f32 v[70:71], v[182:183], v[70:71]
	v_exp_f32_e32 v191, v72
	v_sub_f32_e32 v72, v82, v225
	v_pk_add_f32 v[70:71], v[184:185], v[70:71]
	v_exp_f32_e32 v95, v72
	v_sub_f32_e32 v72, v83, v225
	v_pk_add_f32 v[70:71], v[186:187], v[70:71]
	v_exp_f32_e32 v97, v72
	v_sub_f32_e32 v72, v84, v225
	v_exp_f32_e32 v99, v72
	v_sub_f32_e32 v72, v85, v225
	v_pk_add_f32 v[70:71], v[188:189], v[70:71]
	v_exp_f32_e32 v101, v72
	v_sub_f32_e32 v72, v86, v225
	v_pk_add_f32 v[70:71], v[190:191], v[70:71]
	v_exp_f32_e32 v103, v72
	v_sub_f32_e32 v72, v87, v225
	v_pk_add_f32 v[70:71], v[94:95], v[70:71]
	v_exp_f32_e32 v173, v72
	v_sub_f32_e32 v72, v88, v225
	v_pk_add_f32 v[70:71], v[96:97], v[70:71]
	v_exp_f32_e32 v105, v72
	v_sub_f32_e32 v72, v89, v225
	v_pk_add_f32 v[70:71], v[98:99], v[70:71]
	v_exp_f32_e32 v175, v72
	v_pk_add_f32 v[70:71], v[100:101], v[70:71]
	v_mov_b32_e32 v78, v147
	v_pk_add_f32 v[70:71], v[102:103], v[70:71]
	v_pk_mul_f32 v[72:73], v[48:49], v[78:79] op_sel_hi:[1,0]
	v_pk_add_f32 v[70:71], v[172:173], v[70:71]
	v_pk_mul_f32 v[76:77], v[44:45], v[78:79] op_sel_hi:[1,0]
	v_pk_add_f32 v[70:71], v[104:105], v[70:71]
	v_pk_mul_f32 v[74:75], v[42:43], v[78:79] op_sel_hi:[1,0]
	v_pk_add_f32 v[70:71], v[174:175], v[70:71]
	v_pk_mul_f32 v[48:49], v[52:53], v[78:79] op_sel_hi:[1,0]
	v_pk_fma_f32 v[168:169], v[168:169], v[146:147], v[70:71]
	v_add3_u32 v146, s65, v210, v213
	v_pk_mul_f32 v[70:71], v[46:47], v[78:79] op_sel_hi:[1,0]
	v_pk_mul_f32 v[46:47], v[50:51], v[78:79] op_sel_hi:[1,0]
	v_pk_mul_f32 v[44:45], v[56:57], v[78:79] op_sel_hi:[1,0]
	v_pk_mul_f32 v[42:43], v[54:55], v[78:79] op_sel_hi:[1,0]
	v_cvt_pk_bf16_f32 v50, v176, v178
	v_cvt_pk_bf16_f32 v51, v180, v182
	v_cvt_pk_bf16_f32 v52, v184, v186
	v_cvt_pk_bf16_f32 v53, v188, v190
	v_cvt_pk_bf16_f32 v54, v177, v179
	v_cvt_pk_bf16_f32 v55, v181, v183
	v_cvt_pk_bf16_f32 v56, v185, v187
	v_cvt_pk_bf16_f32 v57, v189, v191
	ds_read_b64_tr_b16 v[80:81], v146 offset:11776
	ds_read_b64_tr_b16 v[78:79], v146 offset:9216
	ds_read_b64_tr_b16 v[82:83], v146 offset:9248
	ds_read_b64_tr_b16 v[84:85], v146 offset:11808
	s_waitcnt lgkmcnt(2)
; #define LAS __attribute__((address_space(3)))
; #define MFMA16(a_, b_, c_) __builtin_amdgcn_mfma_f32_16x16x32_bf16((a_), (b_), (c_), 0, 0, 0)
; __device__ __forceinline__ s16x4 tr_read(LAS unsigned char* p) { return __builtin_bit_cast(s16x4, __builtin_amdgcn_ds_read_tr16_b64_v4i16((LAS v4i16_t*)p)); }
; __device__ __forceinline__ bf16x8 pack8(const f32x4& lo, const f32x4& hi) { u32x4 w; w.x = cvt_pk_bf16(lo[0], lo[1]); w.y = cvt_pk_bf16(lo[2], lo[3]); w.z = cvt_pk_bf16(hi[0], hi[1]); w.w = cvt_pk_bf16(hi[2], hi[3]); return __builtin_bit_cast(bf16x8, w); }
; __device__ __forceinline__ void attn_prompt_unit(ArgsK& a, LAS unsigned char* lds, int b, int h, int qb, int tid, int wave, int lane) {
;     ...
; #pragma unroll
;             for (int c = 0; c < 2; ++c) { bf16x8 pf[2];
; #pragma unroll
;                 for (int qq = 0; qq < 2; ++qq) pf[qq] = pack8(st[2 * c][qq], st[2 * c + 1][qq]);
; #pragma unroll
;                 for (int d = 0; d < 4; ++d) { LAS unsigned char* vp = bufc + AT_V + (32 * c + quad * 4 + (l15 >> 2)) * 160 + d * 32 + (lane & 3) * 8;
;                     const s16x4 r1 = tr_read(vp), r2 = tr_read(vp + 16 * 160);
;                     const bf16x8 vf = (bf16x8){r1[0], r1[1], r1[2], r1[3], r2[0], r2[1], r2[2], r2[3]};
; #pragma unroll
;                     for (int qq = 0; qq < 2; ++qq) o[qq][d] = MFMA16(vf, pf[qq], o[qq][d]); } }
	v_mfma_f32_16x16x32_bf16 v[66:69], v[78:81], v[50:53], v[66:69]
	v_mfma_f32_16x16x32_bf16 v[70:73], v[78:81], v[54:57], v[70:73]
	s_waitcnt lgkmcnt(0)
	v_mfma_f32_16x16x32_bf16 v[78:81], v[82:85], v[50:53], v[90:93]
	v_mfma_f32_16x16x32_bf16 v[74:77], v[82:85], v[54:57], v[74:77]
	ds_read_b64_tr_b16 v[82:83], v146 offset:9280
	ds_read_b64_tr_b16 v[84:85], v146 offset:11840
	s_waitcnt lgkmcnt(0)
	v_mfma_f32_16x16x32_bf16 v[62:65], v[82:85], v[50:53], v[62:65]
	v_mfma_f32_16x16x32_bf16 v[82:85], v[82:85], v[54:57], v[46:49]
	s_nop 2
	ds_read_b64_tr_b16 v[46:47], v146 offset:9312
	ds_read_b64_tr_b16 v[48:49], v146 offset:11872
	v_cvt_pk_bf16_f32 v90, v94, v96
	v_cvt_pk_bf16_f32 v91, v98, v100
	s_waitcnt lgkmcnt(0)
	v_mfma_f32_16x16x32_bf16 v[86:89], v[46:49], v[50:53], v[58:61]
	v_cvt_pk_bf16_f32 v92, v102, v172
	v_cvt_pk_bf16_f32 v93, v104, v174
	v_cvt_pk_bf16_f32 v94, v95, v97
	v_mfma_f32_16x16x32_bf16 v[54:57], v[46:49], v[54:57], v[42:45]
	v_cvt_pk_bf16_f32 v95, v99, v101
	v_cvt_pk_bf16_f32 v96, v103, v173
	v_cvt_pk_bf16_f32 v97, v105, v175
	s_nop 2
	ds_read_b64_tr_b16 v[44:45], v146 offset:16896
	ds_read_b64_tr_b16 v[42:43], v146 offset:14336
	ds_read_b64_tr_b16 v[50:51], v146 offset:14368
	ds_read_b64_tr_b16 v[52:53], v146 offset:16928
	s_waitcnt lgkmcnt(2)
	v_mfma_f32_16x16x32_bf16 v[66:69], v[42:45], v[90:93], v[66:69]
	v_mov_b32_e32 v173, v225
	v_mov_b32_e32 v172, v0
	v_mfma_f32_16x16x32_bf16 v[46:49], v[42:45], v[94:97], v[70:73]
	s_waitcnt lgkmcnt(0)
	v_mfma_f32_16x16x32_bf16 v[58:61], v[50:53], v[90:93], v[78:81]
	v_mfma_f32_16x16x32_bf16 v[42:45], v[50:53], v[94:97], v[74:77]
	ds_read_b64_tr_b16 v[50:51], v146 offset:14400
	ds_read_b64_tr_b16 v[52:53], v146 offset:16960
	s_nop 0
	ds_read_b64_tr_b16 v[74:75], v146 offset:14432
	ds_read_b64_tr_b16 v[76:77], v146 offset:16992
	s_waitcnt lgkmcnt(2)
	v_mfma_f32_16x16x32_bf16 v[62:65], v[50:53], v[90:93], v[62:65]
	v_mfma_f32_16x16x32_bf16 v[50:53], v[50:53], v[94:97], v[82:85]
	s_waitcnt lgkmcnt(0)
	v_mfma_f32_16x16x32_bf16 v[70:73], v[74:77], v[90:93], v[86:89]
	v_mfma_f32_16x16x32_bf16 v[54:57], v[74:77], v[94:97], v[54:57]
	s_add_i32 s14, s35, -1
	s_cmp_ge_u32 s14, s58
	s_cbranch_scc1 .LBB0_256

; __device__ __forceinline__ void attn_prompt_unit(ArgsK& a, LAS unsigned char* lds, int b, int h, int qb, int tid, int wave, int lane) {
;     ...
;             for (int qq = 0; qq < 2; ++qq) { float mx = fmaxf(fmaxf(st[0][qq][0], st[0][qq][1]), fmaxf(st[0][qq][2], st[0][qq][3]));
; #pragma unroll
;                 for (int kb = 1; kb < 4; ++kb) mx = fmaxf(mx, fmaxf(fmaxf(st[kb][qq][0], st[kb][qq][1]), fmaxf(st[kb][qq][2], st[kb][qq][3])));
;                 mx = xmax16_32(mx);
;                 const float mnew = fmaxf(mrun[qq], mx), alpha = __builtin_amdgcn_exp2f(mrun[qq] - mnew); mrun[qq] = mnew; float ps = 0.f;
; #pragma unroll
;                 for (int kb = 0; kb < 4; ++kb)
; #pragma unroll
;                     for (int j = 0; j < 4; ++j) { const float p = __builtin_amdgcn_exp2f(st[kb][qq][j] - mnew); st[kb][qq][j] = p; ps += p; }
;                 lrun[qq] = lrun[qq] * alpha + ps;
; #pragma unroll
;                 for (int d = 0; d < 4; ++d) o[qq][d] = o[qq][d] * alpha; }
.LBB0_269:
	s_nop 2
	v_max3_f32 v141, v90, v91, v92
	v_max3_f32 v142, v93, v94, v95
	v_max3_f32 v141, v141, v96, v97
	v_max3_f32 v142, v142, v98, v99
	v_max3_f32 v141, v141, v100, v101
	v_max3_f32 v142, v142, v102, v103
	v_max3_f32 v141, v141, v104, v105
	v_max_f32_e32 v141, v141, v142
	v_mov_b32_e32 v142, v141
	s_nop 1
	v_permlane16_swap_b32_e32 v141, v142
	v_max_f32_e32 v141, v141, v142
	v_mov_b32_e32 v142, v141
	s_nop 1
	v_permlane32_swap_b32_e32 v141, v142
	v_max3_f32 v182, v140, v141, v142
	v_sub_f32_e32 v90, v90, v182
	v_exp_f32_e32 v164, v90
	v_sub_f32_e32 v90, v91, v182
	v_exp_f32_e32 v166, v90
	v_sub_f32_e32 v90, v92, v182
	v_exp_f32_e32 v168, v90
	v_sub_f32_e32 v90, v93, v182
	v_exp_f32_e32 v170, v90
	v_sub_f32_e32 v90, v94, v182
	v_exp_f32_e32 v172, v90
	v_sub_f32_e32 v90, v95, v182
	v_exp_f32_e32 v174, v90
	v_sub_f32_e32 v90, v96, v182
	v_exp_f32_e32 v176, v90
	v_sub_f32_e32 v90, v97, v182
	v_exp_f32_e32 v178, v90
	v_sub_f32_e32 v90, v98, v182
	v_sub_f32_e32 v140, v140, v182
	v_exp_f32_e32 v98, v90
	v_sub_f32_e32 v90, v99, v182
	v_exp_f32_e32 v146, v140
	v_exp_f32_e32 v140, v90
	v_sub_f32_e32 v90, v100, v182
	v_exp_f32_e32 v100, v90
	v_sub_f32_e32 v90, v101, v182
	v_exp_f32_e32 v142, v90
	v_sub_f32_e32 v90, v102, v182
	v_exp_f32_e32 v102, v90
	v_sub_f32_e32 v90, v103, v182
	v_exp_f32_e32 v144, v90
	v_sub_f32_e32 v90, v104, v182
	v_exp_f32_e32 v104, v90
	v_sub_f32_e32 v90, v105, v182
	v_exp_f32_e32 v162, v90
	v_pk_mul_f32 v[90:91], v[54:55], v[146:147] op_sel_hi:[1,0]
	v_pk_mul_f32 v[54:55], v[58:59], v[146:147] op_sel_hi:[1,0]
	v_pk_mul_f32 v[92:93], v[56:57], v[146:147] op_sel_hi:[1,0]
	v_pk_mul_f32 v[56:57], v[60:61], v[146:147] op_sel_hi:[1,0]
	v_max3_f32 v58, v74, v75, v76
	v_max3_f32 v59, v77, v78, v79
	v_max3_f32 v58, v58, v80, v81
	v_max3_f32 v59, v59, v82, v83
	v_max3_f32 v58, v58, v84, v85
	v_max3_f32 v59, v59, v86, v87
	v_max3_f32 v58, v58, v88, v89
	v_max_f32_e32 v58, v58, v59
	v_mov_b32_e32 v59, v58
	s_nop 1
	v_permlane16_swap_b32_e32 v58, v59
	v_max_f32_e32 v58, v58, v59
	v_mov_b32_e32 v59, v58
	s_nop 1
	v_permlane32_swap_b32_e32 v58, v59
	v_max3_f32 v183, v0, v58, v59
	v_sub_f32_e32 v0, v0, v183
	v_pk_mul_f32 v[96:97], v[52:53], v[146:147] op_sel_hi:[1,0]
	v_pk_mul_f32 v[94:95], v[50:51], v[146:147] op_sel_hi:[1,0]
	v_pk_mul_f32 v[52:53], v[64:65], v[146:147] op_sel_hi:[1,0]
	v_pk_mul_f32 v[50:51], v[62:63], v[146:147] op_sel_hi:[1,0]
	v_exp_f32_e32 v147, v0
	v_sub_f32_e32 v0, v78, v183
	v_exp_f32_e32 v165, v0
	v_sub_f32_e32 v0, v79, v183
	v_exp_f32_e32 v167, v0
	v_sub_f32_e32 v0, v80, v183
	v_exp_f32_e32 v169, v0
	v_sub_f32_e32 v0, v81, v183
	v_exp_f32_e32 v171, v0
	v_sub_f32_e32 v0, v74, v183
	v_exp_f32_e32 v173, v0
	v_sub_f32_e32 v0, v75, v183
	v_pk_add_f32 v[58:59], v[164:165], 0 op_sel_hi:[1,0]
	v_exp_f32_e32 v175, v0
	v_pk_add_f32 v[58:59], v[166:167], v[58:59]
	v_sub_f32_e32 v0, v76, v183
	v_pk_add_f32 v[58:59], v[168:169], v[58:59]
	v_exp_f32_e32 v177, v0
	v_sub_f32_e32 v0, v77, v183
	v_pk_add_f32 v[58:59], v[170:171], v[58:59]
	v_exp_f32_e32 v179, v0
	v_sub_f32_e32 v0, v82, v183
	v_pk_add_f32 v[58:59], v[172:173], v[58:59]
	v_exp_f32_e32 v99, v0
	v_sub_f32_e32 v0, v83, v183
	v_pk_add_f32 v[58:59], v[174:175], v[58:59]
	v_exp_f32_e32 v141, v0
	v_sub_f32_e32 v0, v84, v183
	v_exp_f32_e32 v101, v0
	v_sub_f32_e32 v0, v85, v183
	v_pk_add_f32 v[58:59], v[176:177], v[58:59]
	v_exp_f32_e32 v143, v0
	v_sub_f32_e32 v0, v86, v183
	v_pk_add_f32 v[58:59], v[178:179], v[58:59]
	v_exp_f32_e32 v103, v0
	v_sub_f32_e32 v0, v87, v183
	v_pk_add_f32 v[58:59], v[98:99], v[58:59]
	v_exp_f32_e32 v145, v0
	v_sub_f32_e32 v0, v88, v183
	v_pk_add_f32 v[58:59], v[140:141], v[58:59]
	v_exp_f32_e32 v105, v0
	v_sub_f32_e32 v0, v89, v183
	v_pk_add_f32 v[58:59], v[100:101], v[58:59]
	v_exp_f32_e32 v163, v0
	v_pk_add_f32 v[58:59], v[142:143], v[58:59]
	v_mov_b32_e32 v0, v147
	v_pk_add_f32 v[58:59], v[102:103], v[58:59]
	v_pk_mul_f32 v[60:61], v[32:33], v[0:1] op_sel_hi:[1,0]
	v_pk_add_f32 v[58:59], v[144:145], v[58:59]
	v_pk_mul_f32 v[64:65], v[28:29], v[0:1] op_sel_hi:[1,0]
	v_pk_add_f32 v[58:59], v[104:105], v[58:59]
	v_pk_mul_f32 v[62:63], v[26:27], v[0:1] op_sel_hi:[1,0]
	v_pk_add_f32 v[58:59], v[162:163], v[58:59]
	v_pk_mul_f32 v[32:33], v[44:45], v[0:1] op_sel_hi:[1,0]
	v_pk_fma_f32 v[134:135], v[134:135], v[146:147], v[58:59]
	v_pk_mul_f32 v[58:59], v[30:31], v[0:1] op_sel_hi:[1,0]
	v_pk_mul_f32 v[30:31], v[42:43], v[0:1] op_sel_hi:[1,0]
	v_pk_mul_f32 v[28:29], v[48:49], v[0:1] op_sel_hi:[1,0]
	v_pk_mul_f32 v[26:27], v[46:47], v[0:1] op_sel_hi:[1,0]
	v_add3_u32 v0, s19, v210, v213
	v_cvt_pk_bf16_f32 v42, v164, v166
	v_cvt_pk_bf16_f32 v43, v168, v170
	v_cvt_pk_bf16_f32 v44, v172, v174
	v_cvt_pk_bf16_f32 v45, v176, v178
	v_cvt_pk_bf16_f32 v46, v165, v167
	v_cvt_pk_bf16_f32 v47, v169, v171
	v_cvt_pk_bf16_f32 v48, v173, v175
	v_cvt_pk_bf16_f32 v49, v177, v179
	ds_read_b64_tr_b16 v[76:77], v0 offset:11776
	ds_read_b64_tr_b16 v[74:75], v0 offset:9216
	ds_read_b64_tr_b16 v[78:79], v0 offset:9248
	ds_read_b64_tr_b16 v[80:81], v0 offset:11808
	s_waitcnt lgkmcnt(2)
; #define LAS __attribute__((address_space(3)))
; #define MFMA16(a_, b_, c_) __builtin_amdgcn_mfma_f32_16x16x32_bf16((a_), (b_), (c_), 0, 0, 0)
; __device__ __forceinline__ s16x4 tr_read(LAS unsigned char* p) { return __builtin_bit_cast(s16x4, __builtin_amdgcn_ds_read_tr16_b64_v4i16((LAS v4i16_t*)p)); }
; __device__ __forceinline__ bf16x8 pack8(const f32x4& lo, const f32x4& hi) { u32x4 w; w.x = cvt_pk_bf16(lo[0], lo[1]); w.y = cvt_pk_bf16(lo[2], lo[3]); w.z = cvt_pk_bf16(hi[0], hi[1]); w.w = cvt_pk_bf16(hi[2], hi[3]); return __builtin_bit_cast(bf16x8, w); }
; __device__ __forceinline__ void attn_prompt_unit(ArgsK& a, LAS unsigned char* lds, int b, int h, int qb, int tid, int wave, int lane) {
;     ...
; #pragma unroll
;             for (int c = 0; c < 2; ++c) { bf16x8 pf[2];
; #pragma unroll
;                 for (int qq = 0; qq < 2; ++qq) pf[qq] = pack8(st[2 * c][qq], st[2 * c + 1][qq]);
; #pragma unroll
;                 for (int d = 0; d < 4; ++d) { LAS unsigned char* vp = bufc + AT_V + (32 * c + quad * 4 + (l15 >> 2)) * 160 + d * 32 + (lane & 3) * 8;
;                     const s16x4 r1 = tr_read(vp), r2 = tr_read(vp + 16 * 160);
;                     const bf16x8 vf = (bf16x8){r1[0], r1[1], r1[2], r1[3], r2[0], r2[1], r2[2], r2[3]};
; #pragma unroll
;                     for (int qq = 0; qq < 2; ++qq) o[qq][d] = MFMA16(vf, pf[qq], o[qq][d]); } }
	v_mfma_f32_16x16x32_bf16 v[82:85], v[74:77], v[42:45], v[90:93]
	v_mfma_f32_16x16x32_bf16 v[58:61], v[74:77], v[46:49], v[58:61]
	s_waitcnt lgkmcnt(0)
	v_mfma_f32_16x16x32_bf16 v[74:77], v[78:81], v[42:45], v[94:97]
	v_mfma_f32_16x16x32_bf16 v[62:65], v[78:81], v[46:49], v[62:65]
	ds_read_b64_tr_b16 v[78:79], v0 offset:9280
	ds_read_b64_tr_b16 v[80:81], v0 offset:11840
	s_waitcnt lgkmcnt(0)
	v_mfma_f32_16x16x32_bf16 v[86:89], v[78:81], v[42:45], v[54:57]
	v_mfma_f32_16x16x32_bf16 v[78:81], v[78:81], v[46:49], v[30:33]
	s_nop 2
	ds_read_b64_tr_b16 v[30:31], v0 offset:9312
	ds_read_b64_tr_b16 v[32:33], v0 offset:11872
	v_cvt_pk_bf16_f32 v94, v98, v140
	v_cvt_pk_bf16_f32 v95, v100, v142
	s_waitcnt lgkmcnt(0)
	v_mfma_f32_16x16x32_bf16 v[90:93], v[30:33], v[42:45], v[50:53]
	v_cvt_pk_bf16_f32 v96, v102, v144
	v_cvt_pk_bf16_f32 v97, v104, v162
	v_cvt_pk_bf16_f32 v98, v99, v141
	v_mfma_f32_16x16x32_bf16 v[46:49], v[30:33], v[46:49], v[26:29]
	v_cvt_pk_bf16_f32 v99, v101, v143
	v_cvt_pk_bf16_f32 v100, v103, v145
	v_cvt_pk_bf16_f32 v101, v105, v163
	s_nop 2
	ds_read_b64_tr_b16 v[28:29], v0 offset:16896
	ds_read_b64_tr_b16 v[26:27], v0 offset:14336
	ds_read_b64_tr_b16 v[42:43], v0 offset:14368
	ds_read_b64_tr_b16 v[44:45], v0 offset:16928
	s_waitcnt lgkmcnt(2)
	v_mfma_f32_16x16x32_bf16 v[54:57], v[26:29], v[94:97], v[82:85]
	v_mov_b32_e32 v140, v182
	v_mfma_f32_16x16x32_bf16 v[30:33], v[26:29], v[98:101], v[58:61]
	s_waitcnt lgkmcnt(0)
	v_mfma_f32_16x16x32_bf16 v[50:53], v[42:45], v[94:97], v[74:77]
	v_mfma_f32_16x16x32_bf16 v[26:29], v[42:45], v[98:101], v[62:65]
	ds_read_b64_tr_b16 v[42:43], v0 offset:14400
	ds_read_b64_tr_b16 v[44:45], v0 offset:16960
	ds_read_b64_tr_b16 v[74:75], v0 offset:14432
	ds_read_b64_tr_b16 v[76:77], v0 offset:16992
	v_mov_b32_e32 v0, v183
	s_waitcnt lgkmcnt(2)
	v_mfma_f32_16x16x32_bf16 v[58:61], v[42:45], v[94:97], v[86:89]
	v_mfma_f32_16x16x32_bf16 v[42:45], v[42:45], v[98:101], v[78:81]
	s_waitcnt lgkmcnt(0)
	v_mfma_f32_16x16x32_bf16 v[62:65], v[74:77], v[94:97], v[90:93]
	v_mfma_f32_16x16x32_bf16 v[46:49], v[74:77], v[98:101], v[46:49]

; __device__ __forceinline__ void attn_prompt_unit(ArgsK& a, LAS unsigned char* lds, int b, int h, int qb, int tid, int wave, int lane) {
;     ...
;             for (int qq = 0; qq < 2; ++qq) { float mx = fmaxf(fmaxf(st[0][qq][0], st[0][qq][1]), fmaxf(st[0][qq][2], st[0][qq][3]));
; #pragma unroll
;                 for (int kb = 1; kb < 4; ++kb) mx = fmaxf(mx, fmaxf(fmaxf(st[kb][qq][0], st[kb][qq][1]), fmaxf(st[kb][qq][2], st[kb][qq][3])));
;                 mx = xmax16_32(mx);
;                 const float mnew = fmaxf(mrun[qq], mx), alpha = __builtin_amdgcn_exp2f(mrun[qq] - mnew); mrun[qq] = mnew; float ps = 0.f;
; #pragma unroll
;                 for (int kb = 0; kb < 4; ++kb)
; #pragma unroll
;                     for (int j = 0; j < 4; ++j) { const float p = __builtin_amdgcn_exp2f(st[kb][qq][j] - mnew); st[kb][qq][j] = p; ps += p; }
;                 lrun[qq] = lrun[qq] * alpha + ps;
; #pragma unroll
;                 for (int d = 0; d < 4; ++d) o[qq][d] = o[qq][d] * alpha; }
.LBB0_277:
	s_nop 3
	v_max3_f32 v98, v82, v83, v84
	v_max3_f32 v99, v85, v86, v87
	v_max3_f32 v98, v98, v88, v89
	v_max3_f32 v99, v99, v90, v91
	v_max3_f32 v98, v98, v92, v93
	v_max3_f32 v99, v99, v94, v95
	v_max3_f32 v98, v98, v96, v97
	v_max_f32_e32 v98, v98, v99
	v_mov_b32_e32 v99, v98
	s_nop 1
	v_permlane16_swap_b32_e32 v98, v99
	v_max_f32_e32 v98, v98, v99
	v_mov_b32_e32 v99, v98
	s_nop 1
	v_permlane32_swap_b32_e32 v98, v99
	v_max3_f32 v168, v140, v98, v99
	v_sub_f32_e32 v82, v82, v168
	v_exp_f32_e32 v136, v82
	v_sub_f32_e32 v82, v83, v168
	v_exp_f32_e32 v138, v82
	v_sub_f32_e32 v82, v84, v168
	v_sub_f32_e32 v98, v140, v168
	v_exp_f32_e32 v140, v82
	v_sub_f32_e32 v82, v85, v168
	v_exp_f32_e32 v142, v82
	v_sub_f32_e32 v82, v86, v168
	v_exp_f32_e32 v144, v82
	v_sub_f32_e32 v82, v87, v168
	v_exp_f32_e32 v162, v82
	v_sub_f32_e32 v82, v88, v168
	v_exp_f32_e32 v164, v82
	v_sub_f32_e32 v82, v89, v168
	v_exp_f32_e32 v166, v82
	v_sub_f32_e32 v82, v90, v168
	v_exp_f32_e32 v90, v82
	v_sub_f32_e32 v82, v91, v168
	v_exp_f32_e32 v146, v98
	v_exp_f32_e32 v98, v82
	v_sub_f32_e32 v82, v92, v168
	v_exp_f32_e32 v92, v82
	v_sub_f32_e32 v82, v93, v168
	v_exp_f32_e32 v100, v82
	v_sub_f32_e32 v82, v94, v168
	v_exp_f32_e32 v94, v82
	v_sub_f32_e32 v82, v95, v168
	v_exp_f32_e32 v102, v82
	v_sub_f32_e32 v82, v96, v168
	v_exp_f32_e32 v96, v82
	v_sub_f32_e32 v82, v97, v168
	v_exp_f32_e32 v104, v82
	v_pk_mul_f32 v[82:83], v[54:55], v[146:147] op_sel_hi:[1,0]
	v_pk_mul_f32 v[54:55], v[58:59], v[146:147] op_sel_hi:[1,0]
	v_pk_mul_f32 v[84:85], v[56:57], v[146:147] op_sel_hi:[1,0]
	v_pk_mul_f32 v[56:57], v[60:61], v[146:147] op_sel_hi:[1,0]
	v_max3_f32 v58, v66, v67, v68
	v_max3_f32 v59, v69, v70, v71
	v_max3_f32 v58, v58, v72, v73
	v_max3_f32 v59, v59, v74, v75
	v_max3_f32 v58, v58, v76, v77
	v_max3_f32 v59, v59, v78, v79
	v_max3_f32 v58, v58, v80, v81
	v_max_f32_e32 v58, v58, v59
	v_mov_b32_e32 v59, v58
	s_nop 1
	v_permlane16_swap_b32_e32 v58, v59
	v_max_f32_e32 v58, v58, v59
	v_mov_b32_e32 v59, v58
	s_nop 1
	v_permlane32_swap_b32_e32 v58, v59
	v_max3_f32 v169, v0, v58, v59
	v_sub_f32_e32 v0, v0, v169
	v_pk_mul_f32 v[88:89], v[52:53], v[146:147] op_sel_hi:[1,0]
	v_pk_mul_f32 v[86:87], v[50:51], v[146:147] op_sel_hi:[1,0]
	v_pk_mul_f32 v[52:53], v[64:65], v[146:147] op_sel_hi:[1,0]
	v_pk_mul_f32 v[50:51], v[62:63], v[146:147] op_sel_hi:[1,0]
	v_exp_f32_e32 v147, v0
	v_sub_f32_e32 v0, v70, v169
	v_exp_f32_e32 v137, v0
	v_sub_f32_e32 v0, v71, v169
	v_exp_f32_e32 v139, v0
	v_sub_f32_e32 v0, v72, v169
	v_exp_f32_e32 v141, v0
	v_sub_f32_e32 v0, v73, v169
	v_exp_f32_e32 v143, v0
	v_sub_f32_e32 v0, v66, v169
	v_exp_f32_e32 v145, v0
	v_sub_f32_e32 v0, v67, v169
	v_pk_add_f32 v[58:59], v[136:137], 0 op_sel_hi:[1,0]
	v_exp_f32_e32 v163, v0
	v_pk_add_f32 v[58:59], v[138:139], v[58:59]
	v_sub_f32_e32 v0, v68, v169
	v_pk_add_f32 v[58:59], v[140:141], v[58:59]
	v_exp_f32_e32 v165, v0
	v_sub_f32_e32 v0, v69, v169
	v_pk_add_f32 v[58:59], v[142:143], v[58:59]
	v_exp_f32_e32 v167, v0
	v_sub_f32_e32 v0, v74, v169
	v_pk_add_f32 v[58:59], v[144:145], v[58:59]
	v_exp_f32_e32 v91, v0
	v_sub_f32_e32 v0, v75, v169
	v_pk_add_f32 v[58:59], v[162:163], v[58:59]
	v_exp_f32_e32 v99, v0
	v_sub_f32_e32 v0, v76, v169
	v_exp_f32_e32 v93, v0
	v_sub_f32_e32 v0, v77, v169
	v_pk_add_f32 v[58:59], v[164:165], v[58:59]
	v_exp_f32_e32 v101, v0
	v_sub_f32_e32 v0, v78, v169
	v_pk_add_f32 v[58:59], v[166:167], v[58:59]
	v_exp_f32_e32 v95, v0
	v_sub_f32_e32 v0, v79, v169
	v_pk_add_f32 v[58:59], v[90:91], v[58:59]
	v_exp_f32_e32 v103, v0
	v_sub_f32_e32 v0, v80, v169
	v_pk_add_f32 v[58:59], v[98:99], v[58:59]
	v_exp_f32_e32 v97, v0
	v_sub_f32_e32 v0, v81, v169
	v_pk_add_f32 v[58:59], v[92:93], v[58:59]
	v_exp_f32_e32 v105, v0
	v_pk_add_f32 v[58:59], v[100:101], v[58:59]
	v_mov_b32_e32 v0, v147
	v_pk_add_f32 v[58:59], v[94:95], v[58:59]
	v_pk_mul_f32 v[60:61], v[32:33], v[0:1] op_sel_hi:[1,0]
	v_pk_add_f32 v[58:59], v[102:103], v[58:59]
	v_pk_mul_f32 v[64:65], v[28:29], v[0:1] op_sel_hi:[1,0]
	v_pk_add_f32 v[58:59], v[96:97], v[58:59]
	v_pk_mul_f32 v[62:63], v[26:27], v[0:1] op_sel_hi:[1,0]
	v_pk_add_f32 v[58:59], v[104:105], v[58:59]
	v_pk_mul_f32 v[32:33], v[44:45], v[0:1] op_sel_hi:[1,0]
	v_pk_fma_f32 v[134:135], v[134:135], v[146:147], v[58:59]
	v_pk_mul_f32 v[58:59], v[30:31], v[0:1] op_sel_hi:[1,0]
	v_pk_mul_f32 v[30:31], v[42:43], v[0:1] op_sel_hi:[1,0]
	v_pk_mul_f32 v[28:29], v[48:49], v[0:1] op_sel_hi:[1,0]
	v_pk_mul_f32 v[26:27], v[46:47], v[0:1] op_sel_hi:[1,0]
	v_add3_u32 v0, s19, v210, v213
	v_cvt_pk_bf16_f32 v42, v136, v138
	v_cvt_pk_bf16_f32 v43, v140, v142
	v_cvt_pk_bf16_f32 v44, v144, v162
	v_cvt_pk_bf16_f32 v45, v164, v166
	v_cvt_pk_bf16_f32 v46, v137, v139
	v_cvt_pk_bf16_f32 v47, v141, v143
	v_cvt_pk_bf16_f32 v48, v145, v163
	v_cvt_pk_bf16_f32 v49, v165, v167
	ds_read_b64_tr_b16 v[68:69], v0 offset:11776
	ds_read_b64_tr_b16 v[66:67], v0 offset:9216
	ds_read_b64_tr_b16 v[70:71], v0 offset:9248
	ds_read_b64_tr_b16 v[72:73], v0 offset:11808
	s_waitcnt lgkmcnt(2)
; #define LAS __attribute__((address_space(3)))
; #define MFMA16(a_, b_, c_) __builtin_amdgcn_mfma_f32_16x16x32_bf16((a_), (b_), (c_), 0, 0, 0)
; __device__ __forceinline__ s16x4 tr_read(LAS unsigned char* p) { return __builtin_bit_cast(s16x4, __builtin_amdgcn_ds_read_tr16_b64_v4i16((LAS v4i16_t*)p)); }
; __device__ __forceinline__ bf16x8 pack8(const f32x4& lo, const f32x4& hi) { u32x4 w; w.x = cvt_pk_bf16(lo[0], lo[1]); w.y = cvt_pk_bf16(lo[2], lo[3]); w.z = cvt_pk_bf16(hi[0], hi[1]); w.w = cvt_pk_bf16(hi[2], hi[3]); return __builtin_bit_cast(bf16x8, w); }
; __device__ __forceinline__ void attn_prompt_unit(ArgsK& a, LAS unsigned char* lds, int b, int h, int qb, int tid, int wave, int lane) {
;     ...
; #pragma unroll
;             for (int c = 0; c < 2; ++c) { bf16x8 pf[2];
; #pragma unroll
;                 for (int qq = 0; qq < 2; ++qq) pf[qq] = pack8(st[2 * c][qq], st[2 * c + 1][qq]);
; #pragma unroll
;                 for (int d = 0; d < 4; ++d) { LAS unsigned char* vp = bufc + AT_V + (32 * c + quad * 4 + (l15 >> 2)) * 160 + d * 32 + (lane & 3) * 8;
;                     const s16x4 r1 = tr_read(vp), r2 = tr_read(vp + 16 * 160);
;                     const bf16x8 vf = (bf16x8){r1[0], r1[1], r1[2], r1[3], r2[0], r2[1], r2[2], r2[3]};
; #pragma unroll
;                     for (int qq = 0; qq < 2; ++qq) o[qq][d] = MFMA16(vf, pf[qq], o[qq][d]); } }
	v_mfma_f32_16x16x32_bf16 v[74:77], v[66:69], v[42:45], v[82:85]
	v_mov_b32_e32 v140, v168
	v_mfma_f32_16x16x32_bf16 v[58:61], v[66:69], v[46:49], v[58:61]
	s_waitcnt lgkmcnt(0)
	v_mfma_f32_16x16x32_bf16 v[66:69], v[70:73], v[42:45], v[86:89]
	v_mfma_f32_16x16x32_bf16 v[62:65], v[70:73], v[46:49], v[62:65]
	ds_read_b64_tr_b16 v[70:71], v0 offset:9280
	ds_read_b64_tr_b16 v[72:73], v0 offset:11840
	s_waitcnt lgkmcnt(0)
	v_mfma_f32_16x16x32_bf16 v[78:81], v[70:73], v[42:45], v[54:57]
	v_mfma_f32_16x16x32_bf16 v[70:73], v[70:73], v[46:49], v[30:33]
	s_nop 2
	ds_read_b64_tr_b16 v[30:31], v0 offset:9312
	ds_read_b64_tr_b16 v[32:33], v0 offset:11872
	v_cvt_pk_bf16_f32 v86, v90, v98
	v_cvt_pk_bf16_f32 v87, v92, v100
	s_waitcnt lgkmcnt(0)
	v_mfma_f32_16x16x32_bf16 v[82:85], v[30:33], v[42:45], v[50:53]
	v_cvt_pk_bf16_f32 v88, v94, v102
	v_cvt_pk_bf16_f32 v89, v96, v104
	v_cvt_pk_bf16_f32 v90, v91, v99
	v_mfma_f32_16x16x32_bf16 v[46:49], v[30:33], v[46:49], v[26:29]
	v_cvt_pk_bf16_f32 v91, v93, v101
	v_cvt_pk_bf16_f32 v92, v95, v103
	v_cvt_pk_bf16_f32 v93, v97, v105
	s_nop 2
	ds_read_b64_tr_b16 v[28:29], v0 offset:16896
	ds_read_b64_tr_b16 v[26:27], v0 offset:14336
	ds_read_b64_tr_b16 v[42:43], v0 offset:14368
	ds_read_b64_tr_b16 v[44:45], v0 offset:16928
	s_waitcnt lgkmcnt(2)
	v_mfma_f32_16x16x32_bf16 v[54:57], v[26:29], v[86:89], v[74:77]
	v_mfma_f32_16x16x32_bf16 v[30:33], v[26:29], v[90:93], v[58:61]
	s_waitcnt lgkmcnt(0)
	v_mfma_f32_16x16x32_bf16 v[50:53], v[42:45], v[86:89], v[66:69]
	v_mfma_f32_16x16x32_bf16 v[26:29], v[42:45], v[90:93], v[62:65]
	ds_read_b64_tr_b16 v[42:43], v0 offset:14400
	ds_read_b64_tr_b16 v[44:45], v0 offset:16960
	ds_read_b64_tr_b16 v[66:67], v0 offset:14432
	ds_read_b64_tr_b16 v[68:69], v0 offset:16992
	v_mov_b32_e32 v0, v169
	s_waitcnt lgkmcnt(2)
	v_mfma_f32_16x16x32_bf16 v[58:61], v[42:45], v[86:89], v[78:81]
	v_mfma_f32_16x16x32_bf16 v[42:45], v[42:45], v[90:93], v[70:73]
	s_waitcnt lgkmcnt(0)
	v_mfma_f32_16x16x32_bf16 v[62:65], v[66:69], v[86:89], v[82:85]
	v_mfma_f32_16x16x32_bf16 v[46:49], v[66:69], v[90:93], v[46:49]
